# prepA depthwise-conv rows: 24 conditionally executed single 2-byte loads each followed by vmcnt(0) now load into private temps and are converted after one wait at the join
# speedup vs baseline: 1.3621x; 1.0256x over previous
; DI float bf2f(bf16_t b) { return __uint_as_float(((unsigned)b) << 16); }
; NI void prepA_row(const P& p, int l, int t0) {
;     ...
;     } else if (task < 24) {
;       const bool islru = task < 12;
;       const int sg = islru ? task - 8 : task - 12;
;       const int cbase = sg * 128 + ln, ucol = (islru ? O_BX : O_CQKV) + cbase, cwn = islru ? 512 : 1536;
;       const float* cw = (islru ? p.in[I_LCW] + (size_t)l * 4 * 512 : p.in[I_DCW] + (size_t)l * 4 * 1536) + cbase;
;       float u[RB + 3][4], w[4][4];
; #pragma unroll
;       for (int i = 0; i < RB + 3; ++i) {
;         const int rrow = t0 - 2 + i; const bool ok = rrow >= seg_lo && rrow < seg_hi;
; #pragma unroll
;         for (int j = 0; j < 4; ++j) u[i][j] = ok ? bf2f(U[(size_t)rrow * INP + ucol + 32 * j]) : 0.f;
.LBB0_301:
	v_cmp_lt_i32_e32 vcc, 5, v1
	s_and_saveexec_b64 s[0:1], vcc
	s_xor_b64 s[42:43], exec, s[0:1]
	s_cbranch_execz .LBB0_355
	v_cmp_lt_u32_e32 vcc, 7, v1
	s_and_saveexec_b64 s[0:1], vcc
	s_xor_b64 s[44:45], exec, s[0:1]
	s_cbranch_execz .LBB0_352
	v_cmp_ne_u32_e32 vcc, 24, v1
	s_and_saveexec_b64 s[0:1], vcc
	s_xor_b64 s[46:47], exec, s[0:1]
	s_cbranch_execz .LBB0_347
	v_mov_b32_e32 v178, 0
	v_mov_b32_e32 v179, 0
	v_mov_b32_e32 v180, 0
	v_mov_b32_e32 v181, 0
	v_mov_b32_e32 v182, 0
	v_mov_b32_e32 v183, 0
	v_mov_b32_e32 v184, 0
	v_mov_b32_e32 v185, 0
	v_mov_b32_e32 v186, 0
	v_mov_b32_e32 v190, 0
	v_mov_b32_e32 v191, 0
	v_mov_b32_e32 v192, 0
	v_mov_b32_e32 v193, 0
	v_mov_b32_e32 v194, 0
	v_mov_b32_e32 v195, 0
	v_mov_b32_e32 v196, 0
	v_mov_b32_e32 v197, 0
	v_mov_b32_e32 v198, 0
	v_mov_b32_e32 v199, 0
	v_mov_b32_e32 v200, 0
	v_mov_b32_e32 v201, 0
	v_mov_b32_e32 v202, 0
	v_mov_b32_e32 v203, 0
	v_mov_b32_e32 v218, 0
	v_cmp_gt_u32_e64 s[24:25], 12, v1
	v_readlane_b32 s0, v254, 58
	v_mov_b32_e32 v39, v97
	v_cndmask_b32_e64 v29, -12, -8, s[24:25]
	s_waitcnt vmcnt(7)
	v_add_u32_e32 v65, v29, v1
	v_mov_b32_e32 v29, 0xa00
	v_lshl_or_b32 v96, v65, 7, v0
	v_cndmask_b32_e64 v29, v29, v207, s[24:25]
	v_add_lshl_u32 v38, v96, v29, 1
	v_readlane_b32 s1, v254, 59
	v_readlane_b32 s48, v255, 29
	v_readlane_b32 s49, v255, 30
	v_lshl_add_u64 v[46:47], s[0:1], 0, v[38:39]
	v_readlane_b32 s0, v255, 31
	v_readlane_b32 s1, v255, 32
	v_cndmask_b32_e64 v29, 0, 1, s[48:49]
	v_cmp_lt_u32_e64 s[22:23], 11, v1
	v_lshl_add_u64 v[38:39], v[46:47], 0, s[0:1]
	s_waitcnt vmcnt(4)
	v_mov_b32_e32 v75, 0
	v_cmp_ne_u32_e64 s[0:1], 1, v29
	s_andn2_b64 vcc, exec, s[48:49]
	v_mov_b32_e32 v74, 0
	s_cbranch_vccz .LBB0_357
	s_and_b64 vcc, exec, s[0:1]
	s_cbranch_vccz .LBB0_358

; DI float bf2f(bf16_t b) { return __uint_as_float(((unsigned)b) << 16); }
; NI void prepA_row(const P& p, int l, int t0) {
;     ...
;       for (int i = 0; i < RB + 3; ++i) {
;         const int rrow = t0 - 2 + i; const bool ok = rrow >= seg_lo && rrow < seg_hi;
; #pragma unroll
;         for (int j = 0; j < 4; ++j) u[i][j] = ok ? bf2f(U[(size_t)rrow * INP + ucol + 32 * j]) : 0.f;
;       }
.LBB0_308:
	global_load_ushort v178, v[38:39], off offset:192

; DI float bf2f(bf16_t b) { return __uint_as_float(((unsigned)b) << 16); }
; NI void prepA_row(const P& p, int l, int t0) {
;     ...
;       for (int i = 0; i < RB + 3; ++i) {
;         const int rrow = t0 - 2 + i; const bool ok = rrow >= seg_lo && rrow < seg_hi;
; #pragma unroll
;         for (int j = 0; j < 4; ++j) u[i][j] = ok ? bf2f(U[(size_t)rrow * INP + ucol + 32 * j]) : 0.f;
;       }
.LBB0_313:
	global_load_ushort v179, v[38:39], off offset:192

; DI float bf2f(bf16_t b) { return __uint_as_float(((unsigned)b) << 16); }
; NI void prepA_row(const P& p, int l, int t0) {
;     ...
;       for (int i = 0; i < RB + 3; ++i) {
;         const int rrow = t0 - 2 + i; const bool ok = rrow >= seg_lo && rrow < seg_hi;
; #pragma unroll
;         for (int j = 0; j < 4; ++j) u[i][j] = ok ? bf2f(U[(size_t)rrow * INP + ucol + 32 * j]) : 0.f;
;       }
.LBB0_318:
	global_load_ushort v180, v[42:43], off offset:192

; DI float bf2f(bf16_t b) { return __uint_as_float(((unsigned)b) << 16); }
; NI void prepA_row(const P& p, int l, int t0) {
;     ...
;       for (int i = 0; i < RB + 3; ++i) {
;         const int rrow = t0 - 2 + i; const bool ok = rrow >= seg_lo && rrow < seg_hi;
; #pragma unroll
;         for (int j = 0; j < 4; ++j) u[i][j] = ok ? bf2f(U[(size_t)rrow * INP + ucol + 32 * j]) : 0.f;
;       }
.LBB0_323:
	global_load_ushort v181, v[42:43], off offset:192

; DI float bf2f(bf16_t b) { return __uint_as_float(((unsigned)b) << 16); }
; NI void prepA_row(const P& p, int l, int t0) {
;     ...
;       for (int i = 0; i < RB + 3; ++i) {
;         const int rrow = t0 - 2 + i; const bool ok = rrow >= seg_lo && rrow < seg_hi;
; #pragma unroll
;         for (int j = 0; j < 4; ++j) u[i][j] = ok ? bf2f(U[(size_t)rrow * INP + ucol + 32 * j]) : 0.f;
;       }
.LBB0_328:
	global_load_ushort v182, v[50:51], off offset:192

; DI float bf2f(bf16_t b) { return __uint_as_float(((unsigned)b) << 16); }
; NI void prepA_row(const P& p, int l, int t0) {
;     ...
;       float u[RB + 3][4], w[4][4];
; #pragma unroll
;       for (int i = 0; i < RB + 3; ++i) {
;         const int rrow = t0 - 2 + i; const bool ok = rrow >= seg_lo && rrow < seg_hi;
; #pragma unroll
;         for (int j = 0; j < 4; ++j) u[i][j] = ok ? bf2f(U[(size_t)rrow * INP + ucol + 32 * j]) : 0.f;
;       }
; #pragma unroll
;       for (int tap = 0; tap < 4; ++tap)
; #pragma unroll
;         for (int j = 0; j < 4; ++j) w[tap][j] = cw[tap * cwn + 32 * j];
.LBB0_333:
	global_load_ushort v183, v[50:51], off offset:192
.LBB0_334:
	s_waitcnt vmcnt(0)
	v_lshlrev_b32_e32 v72, 16, v178
	v_lshlrev_b32_e32 v66, 16, v179
	v_lshlrev_b32_e32 v38, 16, v180
	v_lshlrev_b32_e32 v39, 16, v181
	v_lshlrev_b32_e32 v43, 16, v182
	v_lshlrev_b32_e32 v47, 16, v183
	v_lshlrev_b32_e32 v74, 16, v184
	v_lshlrev_b32_e32 v75, 16, v185
	v_lshlrev_b32_e32 v73, 16, v186
	v_lshlrev_b32_e32 v70, 16, v190
	v_lshlrev_b32_e32 v71, 16, v191
	v_lshlrev_b32_e32 v67, 16, v192
	v_lshlrev_b32_e32 v40, 16, v193
	v_lshlrev_b32_e32 v41, 16, v194
	v_lshlrev_b32_e32 v29, 16, v195
	v_lshlrev_b32_e32 v44, 16, v196
	v_lshlrev_b32_e32 v45, 16, v197
	v_lshlrev_b32_e32 v31, 16, v198
	v_lshlrev_b32_e32 v48, 16, v199
	v_lshlrev_b32_e32 v49, 16, v200
	v_lshlrev_b32_e32 v33, 16, v201
	v_lshlrev_b32_e32 v54, 16, v202
	v_lshlrev_b32_e32 v55, 16, v203
	v_lshlrev_b32_e32 v35, 16, v218
	v_mov_b32_e32 v37, 0x200
	v_readlane_b32 s0, v255, 14
	v_cndmask_b32_e64 v42, v207, v37, s[24:25]
	s_waitcnt vmcnt(2)
	v_lshlrev_b32_e32 v69, 16, v68
	v_mov_b32_e32 v37, s0
	v_readlane_b32 s0, v255, 16
	v_lshlrev_b32_e32 v68, 16, v64
	s_waitcnt vmcnt(0)
	v_lshlrev_b32_e32 v64, 16, v77
	v_mov_b32_e32 v46, s0
	v_readlane_b32 s0, v255, 13
	v_cndmask_b32_e64 v51, v37, v46, s[24:25]
	s_nop 0
	v_mov_b32_e32 v37, s0
	v_readlane_b32 s0, v255, 15
	s_nop 1
	v_mov_b32_e32 v46, s0
	v_cndmask_b32_e64 v50, v37, v46, s[24:25]
	v_lshl_add_u64 v[52:53], v[96:97], 2, v[50:51]
	v_lshlrev_b32_e32 v50, 2, v42
	v_mov_b32_e32 v51, v97
	v_lshl_add_u64 v[60:61], v[52:53], 0, v[50:51]
	global_load_dword v56, v[52:53], off
	global_load_dword v57, v[52:53], off offset:128
	global_load_dword v37, v[52:53], off offset:256
	global_load_dword v50, v[52:53], off offset:384
	global_load_dword v58, v[60:61], off
	global_load_dword v59, v[60:61], off offset:128
	global_load_dword v46, v[60:61], off offset:256
	global_load_dword v51, v[60:61], off offset:384
	v_lshlrev_b32_e32 v60, 3, v42
	v_mov_b32_e32 v61, v97
	v_mul_u32_u24_e32 v42, 3, v42
	v_lshl_add_u64 v[62:63], v[52:53], 0, v[60:61]
	v_lshlrev_b32_e32 v60, 2, v42
	v_lshl_add_u64 v[78:79], v[52:53], 0, v[60:61]
	global_load_dword v60, v[62:63], off
	global_load_dword v61, v[62:63], off offset:128
	global_load_dword v80, v[62:63], off offset:256
	global_load_dword v52, v[62:63], off offset:384
	s_nop 0
	global_load_dword v62, v[78:79], off
	global_load_dword v63, v[78:79], off offset:128
	global_load_dword v81, v[78:79], off offset:256
	global_load_dword v53, v[78:79], off offset:384
	v_lshlrev_b32_e32 v42, 16, v76
	s_and_saveexec_b64 s[0:1], s[22:23]
	s_xor_b64 s[0:1], exec, s[0:1]
	s_cbranch_execz .LBB0_344
; DI float siluf(float x) { return x / (1.f + __expf(-x)); }
; NI void prepA_row(const P& p, int l, int t0) {
;     ...
;       } else {
; #pragma unroll
;         for (int rr = 0; rr < RB; ++rr) {
;           float x[4]; float ss = 0.f;
; #pragma unroll
;           for (int j = 0; j < 4; ++j) {
;             float acc = 0.f;
; #pragma unroll
;             for (int tap = 0; tap < 4; ++tap) acc += w[tap][j] * u[rr + tap][j];
;             x[j] = siluf(acc); ss += x[j] * x[j];
;           }
;           if (sg < 8) {
;             ss = hw_sum(ss);
;             float sc = rsqrtf(ss + EPS); if (sg < 4) sc *= 0.08838834764831845f;
; #pragma unroll
;             for (int j = 0; j < 4; ++j) x[j] *= sc;
;           }
	s_waitcnt vmcnt(14)
	v_pk_fma_f32 v[74:75], v[74:75], v[56:57], 0 op_sel_hi:[1,1,0]
	v_cmp_gt_i32_e64 s[24:25], 8, v65
	s_waitcnt vmcnt(10)
	v_pk_fma_f32 v[74:75], v[70:71], v[58:59], v[74:75]
	v_cmp_gt_i32_e64 s[22:23], 4, v65
	s_waitcnt vmcnt(6)
	v_pk_fma_f32 v[74:75], v[60:61], v[68:69], v[74:75]
	s_waitcnt vmcnt(4)
	v_mov_b32_e32 v86, v52
	s_waitcnt vmcnt(2)
	v_pk_fma_f32 v[74:75], v[40:41], v[62:63], v[74:75]
	v_mov_b32_e32 v87, v38
	v_mul_f32_e32 v65, 0xbfb8aa3b, v74
	v_exp_f32_e32 v76, v65
	v_mul_f32_e32 v65, 0xbfb8aa3b, v75
	v_exp_f32_e32 v77, v65
	s_waitcnt vmcnt(1)
	v_mul_f32_e32 v84, v29, v81
	v_pk_add_f32 v[76:77], v[76:77], 1.0 op_sel_hi:[1,0]
	s_nop 0
	v_div_scale_f32 v65, s[48:49], v77, v77, v75
	v_rcp_f32_e32 v78, v65
	s_nop 0
	v_fma_f32 v79, -v65, v78, 1.0
	v_fmac_f32_e32 v78, v79, v78
	v_div_scale_f32 v79, vcc, v75, v77, v75
	v_mul_f32_e32 v82, v79, v78
	v_fma_f32 v83, -v65, v82, v79
	v_fmac_f32_e32 v82, v83, v78
	v_fma_f32 v65, -v65, v82, v79
	v_div_fmas_f32 v65, v65, v78, v82
	v_div_fixup_f32 v77, v65, v77, v75
	v_div_scale_f32 v65, s[48:49], v76, v76, v74
	v_rcp_f32_e32 v75, v65
	s_nop 0
	v_fma_f32 v78, -v65, v75, 1.0
	v_fmac_f32_e32 v75, v78, v75
	v_div_scale_f32 v78, vcc, v74, v76, v74
	v_mul_f32_e32 v79, v78, v75
	v_fma_f32 v82, -v65, v79, v78
	v_fmac_f32_e32 v79, v82, v75
	v_fma_f32 v65, -v65, v79, v78
	v_div_fmas_f32 v65, v65, v75, v79
	v_div_fixup_f32 v76, v65, v76, v74
	v_mul_f32_e32 v74, v73, v37
	v_mov_b32_e32 v73, v66
	v_pk_mul_f32 v[72:73], v[72:73], v[50:51]
	s_waitcnt vmcnt(0)
	v_mov_b32_e32 v65, v53
	v_mov_b32_e32 v75, v72
	v_mul_f32_e32 v78, v67, v46
	v_pk_mul_f32 v[86:87], v[86:87], v[64:65]
	v_pk_add_f32 v[74:75], v[74:75], 0 op_sel_hi:[1,0]
	v_mov_b32_e32 v79, v73
	v_mul_f32_e32 v82, v80, v42
	v_pk_add_f32 v[72:73], v[74:75], v[78:79]
	v_mov_b32_e32 v83, v86
	v_pk_add_f32 v[72:73], v[72:73], v[82:83]
	v_mov_b32_e32 v85, v87
	v_pk_add_f32 v[72:73], v[72:73], v[84:85]
	s_nop 0
	v_mul_f32_e32 v65, 0xbfb8aa3b, v72
	v_exp_f32_e32 v74, v65
	v_mul_f32_e32 v65, 0xbfb8aa3b, v73
	v_exp_f32_e32 v75, v65
	s_nop 0
	v_pk_add_f32 v[74:75], v[74:75], 1.0 op_sel_hi:[1,0]
	s_nop 0
	v_div_scale_f32 v65, s[48:49], v75, v75, v73
	v_rcp_f32_e32 v78, v65
	s_nop 0
	v_fma_f32 v79, -v65, v78, 1.0
	v_fmac_f32_e32 v78, v79, v78
	v_div_scale_f32 v79, vcc, v73, v75, v73
	v_mul_f32_e32 v82, v79, v78
	v_fma_f32 v83, -v65, v82, v79
	v_fmac_f32_e32 v82, v83, v78
	v_fma_f32 v65, -v65, v82, v79
	v_div_fmas_f32 v65, v65, v78, v82
	v_div_fixup_f32 v79, v65, v75, v73
	v_div_scale_f32 v65, s[48:49], v74, v74, v72
	v_rcp_f32_e32 v73, v65
	s_nop 0
	v_fma_f32 v75, -v65, v73, 1.0
	v_fmac_f32_e32 v73, v75, v73
	v_div_scale_f32 v75, vcc, v72, v74, v72
	v_mul_f32_e32 v78, v75, v73
	v_fma_f32 v82, -v65, v78, v75
	v_fmac_f32_e32 v78, v82, v73
	v_fma_f32 v65, -v65, v78, v75
	v_div_fmas_f32 v65, v65, v73, v78
	v_div_fixup_f32 v78, v65, v74, v72
	s_and_saveexec_b64 s[48:49], s[24:25]
	s_cbranch_execz .LBB0_337
	v_pk_mul_f32 v[72:73], v[76:77], v[76:77]
	v_pk_mul_f32 v[74:75], v[78:79], v[78:79]
	v_add_f32_e32 v65, v72, v73
	v_and_b32_e32 v73, 64, v210
	v_xor_b32_e32 v72, 16, v210
	v_add_u32_e32 v73, 64, v73
	v_cmp_lt_i32_e32 vcc, v72, v73
	v_add_f32_e32 v65, v65, v74
	v_add_f32_e32 v65, v65, v75
	v_cndmask_b32_e32 v72, v210, v72, vcc
	v_lshlrev_b32_e32 v72, 2, v72
	ds_bpermute_b32 v72, v72, v65
	s_waitcnt lgkmcnt(0)
	v_add_f32_e32 v65, v65, v72
	v_xor_b32_e32 v72, 8, v210
	v_cmp_lt_i32_e32 vcc, v72, v73
	s_nop 1
	v_cndmask_b32_e32 v72, v210, v72, vcc
	v_lshlrev_b32_e32 v72, 2, v72
	ds_bpermute_b32 v72, v72, v65
	s_waitcnt lgkmcnt(0)
	v_add_f32_e32 v65, v65, v72
	v_xor_b32_e32 v72, 4, v210
	v_cmp_lt_i32_e32 vcc, v72, v73
	s_nop 1
	v_cndmask_b32_e32 v72, v210, v72, vcc
	v_lshlrev_b32_e32 v72, 2, v72
	ds_bpermute_b32 v72, v72, v65
	s_waitcnt lgkmcnt(0)
	v_add_f32_e32 v65, v65, v72
	v_xor_b32_e32 v72, 2, v210
	v_cmp_lt_i32_e32 vcc, v72, v73
	s_nop 1
	v_cndmask_b32_e32 v72, v210, v72, vcc
	v_lshlrev_b32_e32 v72, 2, v72
	ds_bpermute_b32 v72, v72, v65
	s_waitcnt lgkmcnt(0)
	v_add_f32_e32 v65, v65, v72
	v_xor_b32_e32 v72, 1, v210
	v_cmp_lt_i32_e32 vcc, v72, v73
	s_nop 1
	v_cndmask_b32_e32 v72, v210, v72, vcc
	v_lshlrev_b32_e32 v72, 2, v72
	ds_bpermute_b32 v72, v72, v65
	s_waitcnt lgkmcnt(0)
	v_add_f32_e32 v65, v65, v72
	v_add_f32_e32 v65, 0x358637bd, v65
	v_mul_f32_e32 v72, 0x4b800000, v65
	v_cmp_gt_f32_e32 vcc, s77, v65
	s_nop 1
	v_cndmask_b32_e32 v65, v65, v72, vcc
	v_rsq_f32_e32 v65, v65
	s_nop 0
	v_mul_f32_e32 v72, 0x45800000, v65
	v_cndmask_b32_e32 v65, v65, v72, vcc
	v_mul_f32_e32 v72, 0x3db504f3, v65
	v_cndmask_b32_e64 v72, v65, v72, s[22:23]
	v_pk_mul_f32 v[78:79], v[78:79], v[72:73] op_sel_hi:[1,0]
	v_pk_mul_f32 v[76:77], v[76:77], v[72:73] op_sel_hi:[1,0]

; DI float bf2f(bf16_t b) { return __uint_as_float(((unsigned)b) << 16); }
; NI void prepA_row(const P& p, int l, int t0) {
;     ...
;       for (int i = 0; i < RB + 3; ++i) {
;         const int rrow = t0 - 2 + i; const bool ok = rrow >= seg_lo && rrow < seg_hi;
; #pragma unroll
;         for (int j = 0; j < 4; ++j) u[i][j] = ok ? bf2f(U[(size_t)rrow * INP + ucol + 32 * j]) : 0.f;
;       }
.LBB0_357:
	global_load_ushort v184, v[38:39], off
	s_and_b64 vcc, exec, s[0:1]
	s_cbranch_vccnz .LBB0_306
.LBB0_358:
	global_load_ushort v185, v[38:39], off offset:64
	v_mov_b32_e32 v72, 0
	s_and_b64 vcc, exec, s[0:1]
	v_mov_b32_e32 v73, 0
	s_cbranch_vccnz .LBB0_307
.LBB0_359:
	global_load_ushort v186, v[38:39], off offset:128
	s_and_b64 vcc, exec, s[0:1]
	s_cbranch_vccz .LBB0_308
	s_branch .LBB0_309
.LBB0_360:
	global_load_ushort v190, v[38:39], off
	s_and_b64 vcc, exec, s[0:1]
	s_cbranch_vccnz .LBB0_311
.LBB0_361:
	global_load_ushort v191, v[38:39], off offset:64
	v_mov_b32_e32 v66, 0
	s_and_b64 vcc, exec, s[0:1]
	v_mov_b32_e32 v67, 0
	s_cbranch_vccnz .LBB0_312
.LBB0_362:
	global_load_ushort v192, v[38:39], off offset:128
	s_and_b64 vcc, exec, s[0:1]
	s_cbranch_vccz .LBB0_313
	s_branch .LBB0_314
.LBB0_363:
	global_load_ushort v193, v[42:43], off
	s_and_b64 vcc, exec, s[0:1]
	s_cbranch_vccnz .LBB0_316
.LBB0_364:
	global_load_ushort v194, v[42:43], off offset:64
	v_mov_b32_e32 v38, 0
	s_and_b64 vcc, exec, s[0:1]
	v_mov_b32_e32 v29, 0
	s_cbranch_vccnz .LBB0_317
.LBB0_365:
	global_load_ushort v195, v[42:43], off offset:128
	s_and_b64 vcc, exec, s[0:1]
	s_cbranch_vccz .LBB0_318
	s_branch .LBB0_319
.LBB0_366:
	global_load_ushort v196, v[42:43], off
	s_and_b64 vcc, exec, s[0:1]
	s_cbranch_vccnz .LBB0_321
.LBB0_367:
	global_load_ushort v197, v[42:43], off offset:64
	v_mov_b32_e32 v39, 0
	s_and_b64 vcc, exec, s[0:1]
	v_mov_b32_e32 v31, 0
	s_cbranch_vccnz .LBB0_322
.LBB0_368:
	global_load_ushort v198, v[42:43], off offset:128
	s_and_b64 vcc, exec, s[0:1]
	s_cbranch_vccz .LBB0_323
	s_branch .LBB0_324
.LBB0_369:
	global_load_ushort v199, v[50:51], off
	s_and_b64 vcc, exec, s[0:1]
	s_cbranch_vccnz .LBB0_326
.LBB0_370:
	global_load_ushort v200, v[50:51], off offset:64
	v_mov_b32_e32 v43, 0
	s_and_b64 vcc, exec, s[0:1]
	v_mov_b32_e32 v33, 0
	s_cbranch_vccnz .LBB0_327
.LBB0_371:
	global_load_ushort v201, v[50:51], off offset:128
	s_and_b64 vcc, exec, s[0:1]
	s_cbranch_vccz .LBB0_328
	s_branch .LBB0_329
.LBB0_372:
	global_load_ushort v202, v[50:51], off
	s_and_b64 vcc, exec, s[0:1]
	s_cbranch_vccnz .LBB0_331
.LBB0_373:
	global_load_ushort v203, v[50:51], off offset:64
	v_mov_b32_e32 v47, 0
	s_and_b64 vcc, exec, s[0:1]
	v_mov_b32_e32 v35, 0
	s_cbranch_vccnz .LBB0_332
.LBB0_374:
	global_load_ushort v218, v[50:51], off offset:128
	s_and_b64 vcc, exec, s[0:1]
	s_cbranch_vccz .LBB0_333
	s_branch .LBB0_334
